# GLU GEMM: single-tile workgroups hold their x read-modify-write epilogue back ~8 us so the 2-tile workgroups' first epilogue is not bandwidth-starved
# speedup vs baseline: 1.0576x; 1.0038x over previous
.LBB0_422:
	s_add_u32 s54, s52, 0xfffc0080
	s_addc_u32 s55, s53, -1
	s_add_i32 s68, 0, 0x10000
	v_add_u32_e32 v142, s68, v187
	ds_read_b128 v[130:133], v142
	ds_read_b128 v[134:137], v142 offset:1024
	ds_read_b128 v[138:141], v142 offset:2048
	ds_read_b128 v[142:145], v142 offset:3072
	s_cmp_eq_u32 s23, 12
	s_cselect_b32 s57, s5, s55
	s_cselect_b32 s56, s90, s54
	s_cselect_b32 s55, s1, s22
	s_cselect_b32 s54, s91, s94
	v_lshl_add_u64 v[184:185], s[52:53], 0, v[172:173]
	s_add_i32 m0, s41, 0xc000
	ds_read_b128 v[146:149], v189
	ds_read_b128 v[150:153], v189 offset:1024
	ds_read_b128 v[154:157], v189 offset:2048
	ds_read_b128 v[158:161], v189 offset:3072
	ds_read_b128 v[162:165], v189 offset:4096
	ds_read_b128 v[166:169], v189 offset:5120
	ds_read_b128 v[180:183], v189 offset:6144
	ds_read_b128 v[210:213], v189 offset:7168
	global_load_lds_dwordx4 v[184:185], off
	v_lshl_add_u64 v[184:185], s[52:53], 0, v[178:179]
	s_add_i32 m0, s41, 0xe000
	s_nop 0
	global_load_lds_dwordx4 v[184:185], off
	s_waitcnt lgkmcnt(8)
	s_barrier
	s_waitcnt lgkmcnt(0)


	v_mfma_f32_16x16x32_bf16 v[118:121], v[130:133], v[146:149], v[118:121]
	v_mfma_f32_16x16x32_bf16 v[126:129], v[138:141], v[146:149], v[126:129]
	v_mfma_f32_16x16x32_bf16 v[114:117], v[130:133], v[154:157], v[114:117]
	v_mfma_f32_16x16x32_bf16 v[122:125], v[138:141], v[154:157], v[122:125]
	v_mfma_f32_16x16x32_bf16 v[106:109], v[130:133], v[162:165], v[106:109]
	v_mfma_f32_16x16x32_bf16 v[110:113], v[138:141], v[162:165], v[110:113]
	v_mfma_f32_16x16x32_bf16 v[98:101], v[130:133], v[180:183], v[98:101]
	v_mfma_f32_16x16x32_bf16 v[102:105], v[138:141], v[180:183], v[102:105]
	v_mfma_f32_16x16x32_bf16 v[118:121], v[134:137], v[150:153], v[118:121]
	v_mfma_f32_16x16x32_bf16 v[126:129], v[142:145], v[150:153], v[126:129]
	v_mfma_f32_16x16x32_bf16 v[114:117], v[134:137], v[158:161], v[114:117]
	v_mfma_f32_16x16x32_bf16 v[122:125], v[142:145], v[158:161], v[122:125]
	v_mfma_f32_16x16x32_bf16 v[106:109], v[134:137], v[166:169], v[106:109]
	v_mfma_f32_16x16x32_bf16 v[110:113], v[142:145], v[166:169], v[110:113]
	v_mfma_f32_16x16x32_bf16 v[98:101], v[134:137], v[210:213], v[98:101]
	v_mfma_f32_16x16x32_bf16 v[102:105], v[142:145], v[210:213], v[102:105]

	s_barrier
	s_add_i32 s70, 0, 0x14000
	v_add_u32_e32 v184, s70, v187
	s_add_i32 s68, s68, s40
	ds_read_b128 v[214:217], v184
	ds_read_b128 v[218:221], v184 offset:1024
	ds_read_b128 v[222:225], v184 offset:2048
	ds_read_b128 v[226:229], v184 offset:3072
	v_lshl_add_u64 v[184:185], s[54:55], 0, v[0:1]
	s_mov_b32 m0, s68
	v_lshl_add_u64 v[190:191], s[54:55], 0, v[170:171]
	global_load_lds_dwordx4 v[184:185], off
	s_add_i32 m0, s68, 0x2000
	s_nop 0
	global_load_lds_dwordx4 v[190:191], off
	s_barrier
	s_waitcnt lgkmcnt(0)


	v_mfma_f32_16x16x32_bf16 v[66:69], v[214:217], v[146:149], v[66:69]
	v_mfma_f32_16x16x32_bf16 v[70:73], v[222:225], v[146:149], v[70:73]
	v_mfma_f32_16x16x32_bf16 v[50:53], v[214:217], v[154:157], v[50:53]
	v_mfma_f32_16x16x32_bf16 v[54:57], v[222:225], v[154:157], v[54:57]
	v_mfma_f32_16x16x32_bf16 v[42:45], v[214:217], v[162:165], v[42:45]
	v_mfma_f32_16x16x32_bf16 v[46:49], v[222:225], v[162:165], v[46:49]
	v_mfma_f32_16x16x32_bf16 v[34:37], v[214:217], v[180:183], v[34:37]
	v_mfma_f32_16x16x32_bf16 v[38:41], v[222:225], v[180:183], v[38:41]
	v_mfma_f32_16x16x32_bf16 v[66:69], v[218:221], v[150:153], v[66:69]
	v_mfma_f32_16x16x32_bf16 v[70:73], v[226:229], v[150:153], v[70:73]
	v_mfma_f32_16x16x32_bf16 v[50:53], v[218:221], v[158:161], v[50:53]
	v_mfma_f32_16x16x32_bf16 v[54:57], v[226:229], v[158:161], v[54:57]
	v_mfma_f32_16x16x32_bf16 v[42:45], v[218:221], v[166:169], v[42:45]
	v_mfma_f32_16x16x32_bf16 v[46:49], v[226:229], v[166:169], v[46:49]
	v_mfma_f32_16x16x32_bf16 v[34:37], v[218:221], v[210:213], v[34:37]
	v_mfma_f32_16x16x32_bf16 v[38:41], v[226:229], v[210:213], v[38:41]

	s_mov_b32 m0, s41
	v_lshl_add_u64 v[202:203], s[56:57], 0, v[0:1]
	s_barrier
	ds_read_b128 v[146:149], v189 offset:16384
	ds_read_b128 v[150:153], v189 offset:17408
	ds_read_b128 v[154:157], v189 offset:18432
	ds_read_b128 v[158:161], v189 offset:19456
	ds_read_b128 v[162:165], v189 offset:20480
	ds_read_b128 v[166:169], v189 offset:21504
	ds_read_b128 v[180:183], v189 offset:22528
	ds_read_b128 v[210:213], v189 offset:23552
	global_load_lds_dwordx4 v[202:203], off
	v_lshl_add_u64 v[204:205], s[56:57], 0, v[170:171]
	s_mov_b32 m0, s42
	s_nop 0
	global_load_lds_dwordx4 v[204:205], off
	s_barrier
	s_waitcnt lgkmcnt(0)


	v_mfma_f32_16x16x32_bf16 v[90:93], v[130:133], v[146:149], v[90:93]
	v_mfma_f32_16x16x32_bf16 v[94:97], v[138:141], v[146:149], v[94:97]
	v_mfma_f32_16x16x32_bf16 v[82:85], v[130:133], v[154:157], v[82:85]
	v_mfma_f32_16x16x32_bf16 v[86:89], v[138:141], v[154:157], v[86:89]
	v_mfma_f32_16x16x32_bf16 v[74:77], v[130:133], v[162:165], v[74:77]
	v_mfma_f32_16x16x32_bf16 v[78:81], v[138:141], v[162:165], v[78:81]
	v_mfma_f32_16x16x32_bf16 v[58:61], v[130:133], v[180:183], v[58:61]
	v_mfma_f32_16x16x32_bf16 v[62:65], v[138:141], v[180:183], v[62:65]
	v_mfma_f32_16x16x32_bf16 v[90:93], v[134:137], v[150:153], v[90:93]
	v_mfma_f32_16x16x32_bf16 v[94:97], v[142:145], v[150:153], v[94:97]
	v_mfma_f32_16x16x32_bf16 v[82:85], v[134:137], v[158:161], v[82:85]
	v_mfma_f32_16x16x32_bf16 v[86:89], v[142:145], v[158:161], v[86:89]
	v_mfma_f32_16x16x32_bf16 v[74:77], v[134:137], v[166:169], v[74:77]
	v_mfma_f32_16x16x32_bf16 v[78:81], v[142:145], v[166:169], v[78:81]
	v_mfma_f32_16x16x32_bf16 v[58:61], v[134:137], v[210:213], v[58:61]
	v_mfma_f32_16x16x32_bf16 v[62:65], v[142:145], v[210:213], v[62:65]

	s_barrier
	s_add_u32 s68, s54, 0x40000
	s_addc_u32 s69, s55, 0
	s_add_i32 s70, s70, s40
	v_lshl_add_u64 v[130:131], s[68:69], 0, v[0:1]
	s_mov_b32 m0, s70
	s_nop 0
	global_load_lds_dwordx4 v[130:131], off
	v_lshl_add_u64 v[130:131], s[68:69], 0, v[170:171]
	s_add_i32 m0, s70, 0x2000
	s_nop 0
	global_load_lds_dwordx4 v[130:131], off
	s_waitcnt vmcnt(6)
	s_barrier

	v_mfma_f32_16x16x32_bf16 v[26:29], v[214:217], v[146:149], v[26:29]
	v_mfma_f32_16x16x32_bf16 v[30:33], v[222:225], v[146:149], v[30:33]
	v_mfma_f32_16x16x32_bf16 v[18:21], v[214:217], v[154:157], v[18:21]
	v_mfma_f32_16x16x32_bf16 v[22:25], v[222:225], v[154:157], v[22:25]
	v_mfma_f32_16x16x32_bf16 v[10:13], v[214:217], v[162:165], v[10:13]
	v_mfma_f32_16x16x32_bf16 v[14:17], v[222:225], v[162:165], v[14:17]
	v_mfma_f32_16x16x32_bf16 v[2:5], v[214:217], v[180:183], v[2:5]
	v_mfma_f32_16x16x32_bf16 v[6:9], v[222:225], v[180:183], v[6:9]
	v_mfma_f32_16x16x32_bf16 v[26:29], v[218:221], v[150:153], v[26:29]
	v_mfma_f32_16x16x32_bf16 v[30:33], v[226:229], v[150:153], v[30:33]
	v_mfma_f32_16x16x32_bf16 v[18:21], v[218:221], v[158:161], v[18:21]
	v_mfma_f32_16x16x32_bf16 v[22:25], v[226:229], v[158:161], v[22:25]
	v_mfma_f32_16x16x32_bf16 v[10:13], v[218:221], v[166:169], v[10:13]
	v_mfma_f32_16x16x32_bf16 v[14:17], v[226:229], v[166:169], v[14:17]
	v_mfma_f32_16x16x32_bf16 v[2:5], v[218:221], v[210:213], v[2:5]
	v_mfma_f32_16x16x32_bf16 v[6:9], v[226:229], v[210:213], v[6:9]

	s_add_i32 s68, 0, 0x18000
	v_add_u32_e32 v142, s68, v187
	s_barrier
	ds_read_b128 v[130:133], v142
	ds_read_b128 v[134:137], v142 offset:1024
	ds_read_b128 v[138:141], v142 offset:2048
	ds_read_b128 v[142:145], v142 offset:3072
	s_add_u32 s56, s56, 0x40000
	s_addc_u32 s57, s57, 0
	s_mov_b32 m0, s43
	v_lshl_add_u64 v[214:215], s[56:57], 0, v[0:1]
	ds_read_b128 v[146:149], v189 offset:32768
	ds_read_b128 v[150:153], v189 offset:33792
	ds_read_b128 v[154:157], v189 offset:34816
	ds_read_b128 v[158:161], v189 offset:35840
	ds_read_b128 v[162:165], v189 offset:36864
	ds_read_b128 v[166:169], v189 offset:37888
	ds_read_b128 v[180:183], v189 offset:38912
	ds_read_b128 v[210:213], v189 offset:39936
	global_load_lds_dwordx4 v[214:215], off
	v_lshl_add_u64 v[214:215], s[56:57], 0, v[170:171]
	s_mov_b32 m0, s58
	s_nop 0
	global_load_lds_dwordx4 v[214:215], off
	s_waitcnt lgkmcnt(8)
	s_barrier
	s_waitcnt lgkmcnt(0)


	v_mfma_f32_16x16x32_bf16 v[118:121], v[130:133], v[146:149], v[118:121]
	v_mfma_f32_16x16x32_bf16 v[126:129], v[138:141], v[146:149], v[126:129]
	v_mfma_f32_16x16x32_bf16 v[114:117], v[130:133], v[154:157], v[114:117]
	v_mfma_f32_16x16x32_bf16 v[122:125], v[138:141], v[154:157], v[122:125]
	v_mfma_f32_16x16x32_bf16 v[106:109], v[130:133], v[162:165], v[106:109]
	v_mfma_f32_16x16x32_bf16 v[110:113], v[138:141], v[162:165], v[110:113]
	v_mfma_f32_16x16x32_bf16 v[98:101], v[130:133], v[180:183], v[98:101]
	v_mfma_f32_16x16x32_bf16 v[102:105], v[138:141], v[180:183], v[102:105]
	v_mfma_f32_16x16x32_bf16 v[118:121], v[134:137], v[150:153], v[118:121]
	v_mfma_f32_16x16x32_bf16 v[126:129], v[142:145], v[150:153], v[126:129]
	v_mfma_f32_16x16x32_bf16 v[114:117], v[134:137], v[158:161], v[114:117]
	v_mfma_f32_16x16x32_bf16 v[122:125], v[142:145], v[158:161], v[122:125]
	v_mfma_f32_16x16x32_bf16 v[106:109], v[134:137], v[166:169], v[106:109]
	v_mfma_f32_16x16x32_bf16 v[110:113], v[142:145], v[166:169], v[110:113]
	v_mfma_f32_16x16x32_bf16 v[98:101], v[134:137], v[210:213], v[98:101]
	v_mfma_f32_16x16x32_bf16 v[102:105], v[142:145], v[210:213], v[102:105]

	s_barrier
	s_add_i32 s56, 0, 0x1c000
	s_add_i32 s57, s68, s40
	v_add_u32_e32 v209, s56, v187
	v_lshl_add_u64 v[184:185], v[184:185], 0, s[60:61]
	s_mov_b32 m0, s57
	ds_read_b128 v[214:217], v209
	ds_read_b128 v[218:221], v209 offset:1024
	ds_read_b128 v[222:225], v209 offset:2048
	ds_read_b128 v[226:229], v209 offset:3072
	global_load_lds_dwordx4 v[184:185], off
	v_lshl_add_u64 v[184:185], v[190:191], 0, s[60:61]
	s_add_i32 m0, s57, 0x2000
	s_nop 0
	global_load_lds_dwordx4 v[184:185], off
	s_barrier
	s_waitcnt lgkmcnt(0)


	v_mfma_f32_16x16x32_bf16 v[66:69], v[214:217], v[146:149], v[66:69]
	v_mfma_f32_16x16x32_bf16 v[70:73], v[222:225], v[146:149], v[70:73]
	v_mfma_f32_16x16x32_bf16 v[50:53], v[214:217], v[154:157], v[50:53]
	v_mfma_f32_16x16x32_bf16 v[54:57], v[222:225], v[154:157], v[54:57]
	v_mfma_f32_16x16x32_bf16 v[42:45], v[214:217], v[162:165], v[42:45]
	v_mfma_f32_16x16x32_bf16 v[46:49], v[222:225], v[162:165], v[46:49]
	v_mfma_f32_16x16x32_bf16 v[34:37], v[214:217], v[180:183], v[34:37]
	v_mfma_f32_16x16x32_bf16 v[38:41], v[222:225], v[180:183], v[38:41]
	v_mfma_f32_16x16x32_bf16 v[66:69], v[218:221], v[150:153], v[66:69]
	v_mfma_f32_16x16x32_bf16 v[70:73], v[226:229], v[150:153], v[70:73]
	v_mfma_f32_16x16x32_bf16 v[50:53], v[218:221], v[158:161], v[50:53]
	v_mfma_f32_16x16x32_bf16 v[54:57], v[226:229], v[158:161], v[54:57]
	v_mfma_f32_16x16x32_bf16 v[42:45], v[218:221], v[166:169], v[42:45]
	v_mfma_f32_16x16x32_bf16 v[46:49], v[226:229], v[166:169], v[46:49]
	v_mfma_f32_16x16x32_bf16 v[34:37], v[218:221], v[210:213], v[34:37]
	v_mfma_f32_16x16x32_bf16 v[38:41], v[226:229], v[210:213], v[38:41]

	s_mov_b32 m0, s63
	v_lshl_add_u64 v[184:185], v[202:203], 0, s[60:61]
	s_barrier
	ds_read_b128 v[146:149], v189 offset:49152
	ds_read_b128 v[150:153], v189 offset:50176
	ds_read_b128 v[154:157], v189 offset:51200
	ds_read_b128 v[158:161], v189 offset:52224
	ds_read_b128 v[162:165], v189 offset:53248
	ds_read_b128 v[166:169], v189 offset:54272
	ds_read_b128 v[180:183], v189 offset:55296
	ds_read_b128 v[210:213], v189 offset:56320
	global_load_lds_dwordx4 v[184:185], off
	v_lshl_add_u64 v[184:185], v[204:205], 0, s[60:61]
	s_mov_b32 m0, s64
	s_nop 0
	global_load_lds_dwordx4 v[184:185], off
	s_barrier
	s_waitcnt lgkmcnt(0)


	v_mfma_f32_16x16x32_bf16 v[90:93], v[130:133], v[146:149], v[90:93]
	v_mfma_f32_16x16x32_bf16 v[94:97], v[138:141], v[146:149], v[94:97]
	v_mfma_f32_16x16x32_bf16 v[82:85], v[130:133], v[154:157], v[82:85]
	v_mfma_f32_16x16x32_bf16 v[86:89], v[138:141], v[154:157], v[86:89]
	v_mfma_f32_16x16x32_bf16 v[74:77], v[130:133], v[162:165], v[74:77]
	v_mfma_f32_16x16x32_bf16 v[78:81], v[138:141], v[162:165], v[78:81]
	v_mfma_f32_16x16x32_bf16 v[58:61], v[130:133], v[180:183], v[58:61]
	v_mfma_f32_16x16x32_bf16 v[62:65], v[138:141], v[180:183], v[62:65]
	v_mfma_f32_16x16x32_bf16 v[90:93], v[134:137], v[150:153], v[90:93]
	v_mfma_f32_16x16x32_bf16 v[94:97], v[142:145], v[150:153], v[94:97]
	v_mfma_f32_16x16x32_bf16 v[82:85], v[134:137], v[158:161], v[82:85]
	v_mfma_f32_16x16x32_bf16 v[86:89], v[142:145], v[158:161], v[86:89]
	v_mfma_f32_16x16x32_bf16 v[74:77], v[134:137], v[166:169], v[74:77]
	v_mfma_f32_16x16x32_bf16 v[78:81], v[142:145], v[166:169], v[78:81]
	v_mfma_f32_16x16x32_bf16 v[58:61], v[134:137], v[210:213], v[58:61]
	v_mfma_f32_16x16x32_bf16 v[62:65], v[142:145], v[210:213], v[62:65]

	s_barrier
	s_add_u32 s54, s54, 0x40080
	s_addc_u32 s55, s55, 0
	s_add_i32 s56, s56, s40
	v_lshl_add_u64 v[130:131], s[54:55], 0, v[0:1]
	s_mov_b32 m0, s56
	s_nop 0
	global_load_lds_dwordx4 v[130:131], off
	v_lshl_add_u64 v[130:131], s[54:55], 0, v[170:171]
	s_add_i32 m0, s56, 0x2000
	s_nop 0
	global_load_lds_dwordx4 v[130:131], off
	s_waitcnt vmcnt(6)
	s_barrier

	v_mfma_f32_16x16x32_bf16 v[26:29], v[214:217], v[146:149], v[26:29]
	v_mfma_f32_16x16x32_bf16 v[30:33], v[222:225], v[146:149], v[30:33]
	v_mfma_f32_16x16x32_bf16 v[18:21], v[214:217], v[154:157], v[18:21]
	v_mfma_f32_16x16x32_bf16 v[22:25], v[222:225], v[154:157], v[22:25]
	v_mfma_f32_16x16x32_bf16 v[10:13], v[214:217], v[162:165], v[10:13]
	v_mfma_f32_16x16x32_bf16 v[14:17], v[222:225], v[162:165], v[14:17]
	v_mfma_f32_16x16x32_bf16 v[2:5], v[214:217], v[180:183], v[2:5]
	v_mfma_f32_16x16x32_bf16 v[6:9], v[222:225], v[180:183], v[6:9]
	v_mfma_f32_16x16x32_bf16 v[26:29], v[218:221], v[150:153], v[26:29]
	v_mfma_f32_16x16x32_bf16 v[30:33], v[226:229], v[150:153], v[30:33]
	v_mfma_f32_16x16x32_bf16 v[18:21], v[218:221], v[158:161], v[18:21]
	v_mfma_f32_16x16x32_bf16 v[22:25], v[226:229], v[158:161], v[22:25]
	v_mfma_f32_16x16x32_bf16 v[10:13], v[218:221], v[166:169], v[10:13]
	v_mfma_f32_16x16x32_bf16 v[14:17], v[226:229], v[166:169], v[14:17]
	v_mfma_f32_16x16x32_bf16 v[2:5], v[218:221], v[210:213], v[2:5]
	v_mfma_f32_16x16x32_bf16 v[6:9], v[226:229], v[210:213], v[6:9]

	s_add_i32 s23, s23, 2
	s_add_u32 s52, s52, 0x100
	s_addc_u32 s53, s53, 0
	s_add_u32 s94, s94, 0x100
	s_addc_u32 s22, s22, 0
	s_cmp_gt_u32 s23, 13
	s_barrier
	s_cbranch_scc0 .LBB0_422
	s_cmpk_lg_i32 s30, 0x100
	s_cbranch_scc1 .Lglu_epi_go
	s_cmpk_lt_u32 s16, 64
	s_cbranch_scc1 .Lglu_epi_go
	s_sleep 127
	s_sleep 127
.Lglu_epi_go:
	s_sub_i32 s1, s67, 32
	s_lshr_b32 s1, s1, 2
	s_add_i32 s1, s1, 1
	s_cmp_gt_i32 s67, 31
	s_cselect_b32 s1, s1, 0
	v_lshl_or_b32 v134, s66, 7, v188
	v_lshl_add_u32 v130, s67, 8, v186
	s_mul_hi_u32 s5, s1, 0x6000
	s_mulk_i32 s1, 0x6000
	v_ashrrev_i32_e32 v135, 31, v134
	s_add_u32 s22, s59, s1
	v_ashrrev_i32_e32 v131, 31, v130
	v_lshlrev_b64 v[180:181], 2, v[134:135]
	s_addc_u32 s23, s62, s5
	v_lshlrev_b64 v[132:133], 12, v[130:131]
	v_lshl_add_u64 v[134:135], s[26:27], 0, v[180:181]
	v_lshl_add_u64 v[190:191], s[22:23], 0, v[180:181]
	v_lshl_add_u64 v[136:137], v[134:135], 0, v[132:133]
	global_load_dwordx4 v[150:153], v[190:191], off
	global_load_dwordx4 v[210:213], v[136:137], off
	s_mov_b64 s[22:23], 0x80000
	v_or_b32_e32 v138, 16, v130
	v_mul_f32_e32 v131, 0xbfb8aa3b, v122
	v_mul_f32_e32 v141, 0xbfb8aa3b, v124
	v_mul_f32_e32 v125, 0xbfb8aa3b, v125
	v_or_b32_e32 v122, 32, v130
	v_or_b32_e32 v124, 48, v130
	v_lshl_add_u64 v[234:235], v[132:133], 0, s[22:23]
	s_mov_b64 s[22:23], 0x90000
	v_ashrrev_i32_e32 v139, 31, v138
	v_mul_f32_e32 v140, 0xbfb8aa3b, v123
	v_ashrrev_i32_e32 v123, 31, v122
	v_exp_f32_e32 v248, v125
	v_ashrrev_i32_e32 v125, 31, v124
	v_lshl_add_u64 v[238:239], v[132:133], 0, s[22:23]
	s_mov_b64 s[22:23], 0xa0000
	v_lshlrev_b64 v[202:203], 12, v[138:139]
	v_mul_f32_e32 v126, 0xbfb8aa3b, v126
	v_mul_f32_e32 v127, 0xbfb8aa3b, v127
	v_mul_f32_e32 v128, 0xbfb8aa3b, v128
	v_mul_f32_e32 v129, 0xbfb8aa3b, v129
	v_lshlrev_b64 v[204:205], 12, v[122:123]
	v_lshlrev_b64 v[236:237], 12, v[124:125]
	v_lshl_add_u64 v[184:185], v[132:133], 0, s[22:23]
	s_mov_b64 s[22:23], 0xb0000
	v_lshl_add_u64 v[138:139], v[134:135], 0, v[202:203]
	v_exp_f32_e32 v209, v126
	v_exp_f32_e32 v242, v127
	v_lshl_add_u64 v[122:123], v[134:135], 0, v[204:205]
	v_exp_f32_e32 v243, v128
	v_exp_f32_e32 v244, v129
	v_lshl_add_u64 v[182:183], v[132:133], 0, s[22:23]
	v_lshl_add_u64 v[124:125], v[134:135], 0, v[236:237]
	v_lshl_add_u64 v[126:127], v[134:135], 0, v[234:235]
	v_lshl_add_u64 v[128:129], v[134:135], 0, v[238:239]
	global_load_dwordx4 v[214:217], v[138:139], off
	global_load_dwordx4 v[218:221], v[122:123], off
	v_exp_f32_e32 v245, v131
	v_exp_f32_e32 v246, v140
	v_exp_f32_e32 v247, v141
	v_lshl_add_u64 v[240:241], s[26:27], 0, v[132:133]
	v_lshl_add_u64 v[130:131], v[134:135], 0, v[184:185]
	v_lshl_add_u64 v[132:133], v[134:135], 0, v[182:183]
	global_load_dwordx4 v[158:161], v[136:137], off offset:256
	global_load_dwordx4 v[154:157], v[138:139], off offset:256
	global_load_dwordx4 v[146:149], v[122:123], off offset:256
	global_load_dwordx4 v[222:225], v[124:125], off
	global_load_dwordx4 v[142:145], v[124:125], off offset:256
	global_load_dwordx4 v[226:229], v[126:127], off
	s_nop 0
	global_load_dwordx4 v[138:141], v[126:127], off offset:256
	global_load_dwordx4 v[230:233], v[128:129], off
	global_load_dwordx4 v[134:137], v[128:129], off offset:256
	global_load_dwordx4 v[166:169], v[130:131], off
	s_nop 0
	global_load_dwordx4 v[126:129], v[130:131], off offset:256
	global_load_dwordx4 v[162:165], v[132:133], off
	global_load_dwordx4 v[122:125], v[132:133], off offset:256
	v_add_f32_e32 v130, 1.0, v209
	v_add_f32_e32 v131, 1.0, v242
	v_add_f32_e32 v132, 1.0, v243
	v_add_f32_e32 v133, 1.0, v244
	v_add_f32_e32 v209, 1.0, v245
	v_rcp_f32_e32 v242, v130
	v_rcp_f32_e32 v243, v131
	v_rcp_f32_e32 v244, v132
	v_rcp_f32_e32 v245, v133
	global_load_dwordx4 v[130:133], v[190:191], off offset:256
	v_mul_f32_e32 v54, 0xbfb8aa3b, v54
	v_mul_f32_e32 v55, 0xbfb8aa3b, v55
	v_mul_f32_e32 v56, 0xbfb8aa3b, v56
	v_mul_f32_e32 v57, 0xbfb8aa3b, v57
	v_exp_f32_e32 v54, v54
	v_exp_f32_e32 v55, v55
	v_exp_f32_e32 v56, v56
	v_exp_f32_e32 v57, v57
	v_mul_f32_e32 v48, 0xbfb8aa3b, v48
	v_add_f32_e32 v54, 1.0, v54
	v_add_f32_e32 v55, 1.0, v55
	v_add_f32_e32 v56, 1.0, v56
	v_add_f32_e32 v57, 1.0, v57
	v_mul_f32_e32 v46, 0xbfb8aa3b, v46
	v_mul_f32_e32 v47, 0xbfb8aa3b, v47
	v_exp_f32_e32 v48, v48
	v_mul_f32_e32 v49, 0xbfb8aa3b, v49
	v_rcp_f32_e32 v54, v54
	v_rcp_f32_e32 v55, v55
	v_rcp_f32_e32 v56, v56
	v_rcp_f32_e32 v57, v57
	v_exp_f32_e32 v46, v46
	v_exp_f32_e32 v47, v47
	v_exp_f32_e32 v49, v49
	v_mul_f32_e32 v88, 0xbfb8aa3b, v88
	v_mul_f32_e32 v89, 0xbfb8aa3b, v89
	v_exp_f32_e32 v88, v88
	v_exp_f32_e32 v89, v89
	v_mul_f32_e32 v80, 0xbfb8aa3b, v80
	v_mul_f32_e32 v81, 0xbfb8aa3b, v81
	v_exp_f32_e32 v80, v80
	v_exp_f32_e32 v81, v81
	v_add_f32_e32 v48, 1.0, v48
	v_mul_f32_e32 v40, 0xbfb8aa3b, v40
	v_pk_mul_f32 v[54:55], v[50:51], v[54:55]
	v_pk_mul_f32 v[50:51], v[52:53], v[56:57]
	v_add_f32_e32 v46, 1.0, v46
	v_add_f32_e32 v47, 1.0, v47
	v_rcp_f32_e32 v52, v48
	v_add_f32_e32 v48, 1.0, v49
	v_mul_f32_e32 v38, 0xbfb8aa3b, v38
	v_mul_f32_e32 v39, 0xbfb8aa3b, v39
	v_exp_f32_e32 v40, v40
	v_mul_f32_e32 v41, 0xbfb8aa3b, v41
	v_rcp_f32_e32 v46, v46
	v_rcp_f32_e32 v47, v47
	v_rcp_f32_e32 v53, v48
	v_exp_f32_e32 v38, v38
	v_exp_f32_e32 v39, v39
	v_exp_f32_e32 v41, v41
	v_add_f32_e32 v88, 1.0, v88
	v_add_f32_e32 v89, 1.0, v89
	v_rcp_f32_e32 v88, v88
	v_rcp_f32_e32 v89, v89
	v_add_f32_e32 v80, 1.0, v80
	v_add_f32_e32 v81, 1.0, v81
	v_rcp_f32_e32 v80, v80
	v_rcp_f32_e32 v81, v81
	v_add_f32_e32 v40, 1.0, v40
	v_mul_f32_e32 v32, 0xbfb8aa3b, v32
	v_pk_mul_f32 v[46:47], v[42:43], v[46:47]
	v_pk_mul_f32 v[42:43], v[44:45], v[52:53]
	v_add_f32_e32 v38, 1.0, v38
	v_add_f32_e32 v39, 1.0, v39
	v_rcp_f32_e32 v44, v40
	v_add_f32_e32 v40, 1.0, v41
	v_mul_f32_e32 v30, 0xbfb8aa3b, v30
	v_mul_f32_e32 v31, 0xbfb8aa3b, v31
	v_exp_f32_e32 v32, v32
	v_mul_f32_e32 v33, 0xbfb8aa3b, v33
	v_mul_f32_e32 v78, 0xbfb8aa3b, v78
	v_rcp_f32_e32 v38, v38
	v_rcp_f32_e32 v39, v39
	v_rcp_f32_e32 v45, v40
	v_exp_f32_e32 v30, v30
	v_exp_f32_e32 v31, v31
	v_exp_f32_e32 v33, v33
	v_pk_mul_f32 v[84:85], v[84:85], v[88:89]
	v_exp_f32_e32 v88, v78
	v_mul_f32_e32 v78, 0xbfb8aa3b, v79
	v_mul_f32_e32 v62, 0xbfb8aa3b, v62
	v_exp_f32_e32 v89, v78
	v_pk_mul_f32 v[76:77], v[76:77], v[80:81]
	v_exp_f32_e32 v80, v62
	v_mul_f32_e32 v62, 0xbfb8aa3b, v63
	v_exp_f32_e32 v81, v62
	v_mul_f32_e32 v64, 0xbfb8aa3b, v64
	v_mul_f32_e32 v65, 0xbfb8aa3b, v65
	v_add_f32_e32 v32, 1.0, v32
	v_mul_f32_e32 v24, 0xbfb8aa3b, v24
	v_mul_f32_e32 v112, 0xbfb8aa3b, v112
	v_mul_f32_e32 v113, 0xbfb8aa3b, v113
	v_mul_f32_e32 v104, 0xbfb8aa3b, v104
	v_mul_f32_e32 v105, 0xbfb8aa3b, v105
	v_mul_f32_e32 v96, 0xbfb8aa3b, v96
	v_mul_f32_e32 v97, 0xbfb8aa3b, v97
	v_exp_f32_e32 v64, v64
	v_exp_f32_e32 v65, v65
	v_pk_mul_f32 v[38:39], v[34:35], v[38:39]
	v_pk_mul_f32 v[34:35], v[36:37], v[44:45]
	v_add_f32_e32 v30, 1.0, v30
	v_add_f32_e32 v31, 1.0, v31
	v_rcp_f32_e32 v36, v32
	v_add_f32_e32 v32, 1.0, v33
	v_mul_f32_e32 v22, 0xbfb8aa3b, v22
	v_mul_f32_e32 v23, 0xbfb8aa3b, v23
	v_exp_f32_e32 v24, v24
	v_mul_f32_e32 v25, 0xbfb8aa3b, v25
	v_exp_f32_e32 v112, v112
	v_exp_f32_e32 v113, v113
	v_exp_f32_e32 v104, v104
	v_exp_f32_e32 v105, v105
	v_exp_f32_e32 v96, v96
	v_exp_f32_e32 v97, v97
	v_rcp_f32_e32 v30, v30
	v_rcp_f32_e32 v31, v31
	v_rcp_f32_e32 v37, v32
	v_exp_f32_e32 v22, v22
	v_exp_f32_e32 v23, v23
	v_exp_f32_e32 v25, v25
	v_add_f32_e32 v88, 1.0, v88
	v_add_f32_e32 v89, 1.0, v89
	v_rcp_f32_e32 v88, v88
	v_rcp_f32_e32 v89, v89
	v_add_f32_e32 v80, 1.0, v80
	v_add_f32_e32 v81, 1.0, v81
	v_pk_mul_f32 v[118:119], v[118:119], v[242:243]
	v_rcp_f32_e32 v80, v80
	v_rcp_f32_e32 v81, v81
	v_add_f32_e32 v64, 1.0, v64
	v_add_f32_e32 v65, 1.0, v65
	v_add_f32_e32 v24, 1.0, v24
	v_mul_f32_e32 v16, 0xbfb8aa3b, v16
	v_add_f32_e32 v250, 1.0, v247
	v_pk_mul_f32 v[120:121], v[120:121], v[244:245]
	s_waitcnt vmcnt(0)
	v_pk_fma_f32 v[210:211], v[118:119], v[150:151], v[210:211]
	v_add_f32_e32 v118, 1.0, v248
	v_add_f32_e32 v112, 1.0, v112
	v_add_f32_e32 v113, 1.0, v113
	v_add_f32_e32 v104, 1.0, v104
	v_add_f32_e32 v105, 1.0, v105
	v_add_f32_e32 v96, 1.0, v96
	v_add_f32_e32 v97, 1.0, v97
	v_rcp_f32_e32 v64, v64
	v_rcp_f32_e32 v65, v65
	v_pk_mul_f32 v[30:31], v[26:27], v[30:31]
	v_pk_mul_f32 v[26:27], v[28:29], v[36:37]
	v_add_f32_e32 v22, 1.0, v22
	v_add_f32_e32 v23, 1.0, v23
	v_rcp_f32_e32 v28, v24
	v_add_f32_e32 v24, 1.0, v25
	v_mul_f32_e32 v14, 0xbfb8aa3b, v14
	v_mul_f32_e32 v15, 0xbfb8aa3b, v15
	v_exp_f32_e32 v16, v16
	v_mul_f32_e32 v17, 0xbfb8aa3b, v17
	v_pk_fma_f32 v[212:213], v[120:121], v[152:153], v[212:213]
	v_rcp_f32_e32 v120, v250
	v_rcp_f32_e32 v121, v118
	v_rcp_f32_e32 v112, v112
	v_rcp_f32_e32 v113, v113
	v_rcp_f32_e32 v104, v104
	v_rcp_f32_e32 v105, v105
	v_rcp_f32_e32 v96, v96
	v_rcp_f32_e32 v97, v97
	v_rcp_f32_e32 v22, v22
	v_rcp_f32_e32 v23, v23
	v_rcp_f32_e32 v29, v24
	v_exp_f32_e32 v14, v14
	v_exp_f32_e32 v15, v15
	v_exp_f32_e32 v17, v17
	v_pk_mul_f32 v[74:75], v[74:75], v[88:89]
	v_lshl_add_u64 v[62:63], s[26:27], 0, v[184:185]
	v_pk_fma_f32 v[76:77], v[76:77], v[152:153], v[168:169]
	v_pk_fma_f32 v[74:75], v[74:75], v[150:151], v[166:167]
	v_lshl_add_u64 v[62:63], v[62:63], 0, v[180:181]
	v_pk_mul_f32 v[58:59], v[58:59], v[80:81]
	v_mul_f32_e32 v110, 0xbfb8aa3b, v110
	v_mul_f32_e32 v102, 0xbfb8aa3b, v102
	v_mul_f32_e32 v94, 0xbfb8aa3b, v94
	v_mul_f32_e32 v86, 0xbfb8aa3b, v86
	global_store_dwordx4 v[62:63], v[74:77], off
	v_pk_mul_f32 v[60:61], v[60:61], v[64:65]
	v_add_f32_e32 v16, 1.0, v16
	v_pk_fma_f32 v[74:75], v[58:59], v[150:151], v[162:163]
	v_mul_f32_e32 v58, 0xbfb8aa3b, v70
	v_mul_f32_e32 v8, 0xbfb8aa3b, v8
	v_pk_mul_f32 v[116:117], v[116:117], v[120:121]
	v_exp_f32_e32 v120, v110
	v_mul_f32_e32 v110, 0xbfb8aa3b, v111
	v_pk_mul_f32 v[108:109], v[108:109], v[112:113]
	v_exp_f32_e32 v112, v102
	v_mul_f32_e32 v102, 0xbfb8aa3b, v103
	v_pk_mul_f32 v[100:101], v[100:101], v[104:105]
	v_exp_f32_e32 v104, v94
	v_mul_f32_e32 v94, 0xbfb8aa3b, v95
	v_pk_mul_f32 v[92:93], v[92:93], v[96:97]
	v_exp_f32_e32 v96, v86
	v_mul_f32_e32 v86, 0xbfb8aa3b, v87
	v_pk_fma_f32 v[76:77], v[60:61], v[152:153], v[164:165]
	v_exp_f32_e32 v60, v58
	v_mul_f32_e32 v58, 0xbfb8aa3b, v71
	v_mul_f32_e32 v64, 0xbfb8aa3b, v72
	v_mul_f32_e32 v65, 0xbfb8aa3b, v73
	v_pk_mul_f32 v[22:23], v[18:19], v[22:23]
	v_pk_mul_f32 v[18:19], v[20:21], v[28:29]
	v_add_f32_e32 v14, 1.0, v14
	v_add_f32_e32 v15, 1.0, v15
	v_rcp_f32_e32 v20, v16
	v_add_f32_e32 v16, 1.0, v17
	v_mul_f32_e32 v6, 0xbfb8aa3b, v6
	v_mul_f32_e32 v7, 0xbfb8aa3b, v7
	v_exp_f32_e32 v8, v8
	v_mul_f32_e32 v9, 0xbfb8aa3b, v9
	v_exp_f32_e32 v121, v110
	v_exp_f32_e32 v113, v102
	v_exp_f32_e32 v105, v94
	v_exp_f32_e32 v97, v86
	v_exp_f32_e32 v61, v58
	v_exp_f32_e32 v64, v64
	v_exp_f32_e32 v65, v65
	v_rcp_f32_e32 v14, v14
	v_rcp_f32_e32 v15, v15
	v_rcp_f32_e32 v21, v16
	v_exp_f32_e32 v6, v6
	v_exp_f32_e32 v7, v7
	v_exp_f32_e32 v9, v9
	v_add_f32_e32 v8, 1.0, v8
	v_add_f32_e32 v249, 1.0, v246
	v_add_f32_e32 v120, 1.0, v120
	v_add_f32_e32 v121, 1.0, v121
	v_add_f32_e32 v112, 1.0, v112
	v_add_f32_e32 v113, 1.0, v113
	v_add_f32_e32 v104, 1.0, v104
	v_add_f32_e32 v105, 1.0, v105
	v_add_f32_e32 v96, 1.0, v96
	v_add_f32_e32 v97, 1.0, v97
	v_add_f32_e32 v60, 1.0, v60
	v_add_f32_e32 v61, 1.0, v61
	v_add_f32_e32 v64, 1.0, v64
	v_add_f32_e32 v65, 1.0, v65
	v_pk_mul_f32 v[14:15], v[10:11], v[14:15]
	v_pk_mul_f32 v[10:11], v[12:13], v[20:21]
	v_add_f32_e32 v6, 1.0, v6
	v_add_f32_e32 v7, 1.0, v7
	v_rcp_f32_e32 v12, v8
	v_add_f32_e32 v8, 1.0, v9
	v_rcp_f32_e32 v246, v209
	v_rcp_f32_e32 v247, v249
	v_rcp_f32_e32 v120, v120
	v_rcp_f32_e32 v121, v121
	v_rcp_f32_e32 v112, v112
	v_rcp_f32_e32 v113, v113
	v_rcp_f32_e32 v104, v104
	v_rcp_f32_e32 v105, v105
	v_rcp_f32_e32 v96, v96
	v_rcp_f32_e32 v97, v97
	v_rcp_f32_e32 v60, v60
	v_rcp_f32_e32 v61, v61
	v_rcp_f32_e32 v64, v64
	v_rcp_f32_e32 v65, v65
	v_rcp_f32_e32 v6, v6
	v_rcp_f32_e32 v7, v7
	v_rcp_f32_e32 v13, v8
	v_pk_mul_f32 v[114:115], v[114:115], v[246:247]
	v_lshl_add_u64 v[110:111], s[26:27], 0, v[202:203]
	v_pk_mul_f32 v[106:107], v[106:107], v[120:121]
	v_lshl_add_u64 v[102:103], s[26:27], 0, v[204:205]
	v_pk_mul_f32 v[98:99], v[98:99], v[112:113]
	v_lshl_add_u64 v[94:95], s[26:27], 0, v[236:237]
	v_pk_mul_f32 v[90:91], v[90:91], v[104:105]
	v_lshl_add_u64 v[86:87], s[26:27], 0, v[234:235]
	v_pk_mul_f32 v[82:83], v[82:83], v[96:97]
	v_lshl_add_u64 v[78:79], s[26:27], 0, v[238:239]
	v_lshl_add_u64 v[58:59], s[26:27], 0, v[182:183]
	v_pk_mul_f32 v[60:61], v[66:67], v[60:61]
	v_pk_mul_f32 v[64:65], v[68:69], v[64:65]
	v_pk_mul_f32 v[2:3], v[2:3], v[6:7]
	v_pk_mul_f32 v[4:5], v[4:5], v[12:13]
	v_lshl_add_u64 v[118:119], v[240:241], 0, v[180:181]
	v_pk_fma_f32 v[116:117], v[116:117], v[152:153], v[216:217]
	v_pk_fma_f32 v[114:115], v[114:115], v[150:151], v[214:215]
	v_lshl_add_u64 v[110:111], v[110:111], 0, v[180:181]
	v_pk_fma_f32 v[108:109], v[108:109], v[152:153], v[220:221]
	v_pk_fma_f32 v[106:107], v[106:107], v[150:151], v[218:219]
	v_lshl_add_u64 v[102:103], v[102:103], 0, v[180:181]
	v_pk_fma_f32 v[100:101], v[100:101], v[152:153], v[224:225]
	v_pk_fma_f32 v[98:99], v[98:99], v[150:151], v[222:223]
	v_lshl_add_u64 v[94:95], v[94:95], 0, v[180:181]
	v_pk_fma_f32 v[92:93], v[92:93], v[152:153], v[228:229]
	v_pk_fma_f32 v[90:91], v[90:91], v[150:151], v[226:227]
	v_lshl_add_u64 v[86:87], v[86:87], 0, v[180:181]
	v_pk_fma_f32 v[84:85], v[84:85], v[152:153], v[232:233]
	v_pk_fma_f32 v[82:83], v[82:83], v[150:151], v[230:231]
	v_lshl_add_u64 v[78:79], v[78:79], 0, v[180:181]
	v_lshl_add_u64 v[58:59], v[58:59], 0, v[180:181]
	v_pk_fma_f32 v[66:67], v[64:65], v[132:133], v[160:161]
	v_pk_fma_f32 v[64:65], v[60:61], v[130:131], v[158:159]
	v_pk_fma_f32 v[50:51], v[50:51], v[132:133], v[156:157]
	v_pk_fma_f32 v[48:49], v[54:55], v[130:131], v[154:155]
	v_pk_fma_f32 v[42:43], v[42:43], v[132:133], v[148:149]
	v_pk_fma_f32 v[40:41], v[46:47], v[130:131], v[146:147]
	v_pk_fma_f32 v[34:35], v[34:35], v[132:133], v[144:145]
	v_pk_fma_f32 v[32:33], v[38:39], v[130:131], v[142:143]
	v_pk_fma_f32 v[26:27], v[26:27], v[132:133], v[140:141]
	v_pk_fma_f32 v[24:25], v[30:31], v[130:131], v[138:139]
	v_pk_fma_f32 v[18:19], v[18:19], v[132:133], v[136:137]
	v_pk_fma_f32 v[16:17], v[22:23], v[130:131], v[134:135]
	v_pk_fma_f32 v[10:11], v[10:11], v[132:133], v[128:129]
	v_pk_fma_f32 v[8:9], v[14:15], v[130:131], v[126:127]
	v_pk_fma_f32 v[4:5], v[4:5], v[132:133], v[124:125]
	v_pk_fma_f32 v[2:3], v[2:3], v[130:131], v[122:123]
	s_and_b64 vcc, exec, s[2:3]
	s_mov_b32 s66, s0
	s_mov_b32 s67, s4
	s_mov_b64 s[54:55], s[18:19]
	s_mov_b64 s[52:53], s[6:7]
	global_store_dwordx4 v[118:119], v[210:213], off
	global_store_dwordx4 v[110:111], v[114:117], off
	global_store_dwordx4 v[102:103], v[106:109], off
	global_store_dwordx4 v[94:95], v[98:101], off
	global_store_dwordx4 v[86:87], v[90:93], off
	global_store_dwordx4 v[78:79], v[82:85], off
	global_store_dwordx4 v[58:59], v[74:77], off
	global_store_dwordx4 v[118:119], v[64:67], off offset:256
	global_store_dwordx4 v[110:111], v[48:51], off offset:256
	global_store_dwordx4 v[102:103], v[40:43], off offset:256
	global_store_dwordx4 v[94:95], v[32:35], off offset:256
	global_store_dwordx4 v[86:87], v[24:27], off offset:256
	global_store_dwordx4 v[78:79], v[16:19], off offset:256
	global_store_dwordx4 v[62:63], v[8:11], off offset:256
	global_store_dwordx4 v[58:59], v[2:5], off offset:256
	s_cbranch_vccz .LBB0_419
	s_waitcnt vmcnt(0)
	v_readlane_b32 s66, v252, 44
	v_readlane_b32 s64, v254, 62
	s_cmpk_gt_u32 s14, 0xff
	v_readlane_b32 s67, v252, 45
	v_readlane_b32 s65, v254, 63
	s_cbranch_scc1 .LBB0_426
	s_barrier
